# attn-prefetch-wait-exact-store-count
# speedup vs baseline: 1.0016x; 1.0016x over previous
; #define LAS __attribute__((address_space(3)))
; #define X make_ctx(lds_raw)
;     ...
;         __syncthreads();
;         { const int i = X.tid >> 2, c = X.tid & 3; const int t = tb + (128 * n + i) * r; const bf16_t* src = proj + (size_t)t * NMAIN + C_AQ + h * 64 + 16 * c;
;           *(LAS u32x4*)(Qs + i * QP + 16 * c) = *(const u32x4*)src; *(LAS u32x4*)(Qs + i * QP + 16 * c + 8) = *(const u32x4*)(src + 8); }
;         for (int blk = reuse ? 1 : 0; blk < 2; ++blk) {
;             const int half = blk ? cur_half : prev_half;
;             { const int j = X.tid >> 2, c = X.tid & 3; int m = 128 * (n - 1 + blk) + j; m = m < 0 ? 0 : m; const int t = tb + m * r;
;               const bf16_t* src = proj + (size_t)t * NMAIN + C_AK + h * 64 + 16 * c;
;               *(LAS u32x4*)(Ks + (half * 128 + j) * QP + 16 * c) = *(const u32x4*)src; *(LAS u32x4*)(Ks + (half * 128 + j) * QP + 16 * c + 8) = *(const u32x4*)(src + 8); }
.Lapf_steady:
	s_cmp_eq_u32 s98, 5
	s_cbranch_scc1 .Lapf_w5
	s_waitcnt vmcnt(4)

; #define LAS __attribute__((address_space(3)))
;     ...
;         for (int ks = 0; ks < 2; ++ks) bq[ks] = *(const LAS bf16x8*)(Qs + (i0 + fr) * QP + 32 * ks + 8 * fq);
;         f32x4 sc[9];
; #pragma unroll
;         for (int q = 0; q < 9; ++q) { sc[q] = (f32x4){0.f, 0.f, 0.f, 0.f};
; #pragma unroll
;             for (int ks = 0; ks < 2; ++ks) { const bf16x8 ak = *(const LAS bf16x8*)(Ks + (KOFF(w + q) + fr) * QP + 32 * ks + 8 * fq); sc[q] = __builtin_amdgcn_mfma_f32_16x16x32_bf16(ak, bq[ks], sc[q], 0, 0, 0); } }
;         const int iq = i0 + fr;
;         float mx = -INFINITY;
; #pragma unroll
;         for (int q = 0; q < 9; ++q) { const bool tile_ok = (n > 0) || (w + q >= 8);
; #pragma unroll
;             for (int e = 0; e < 4; ++e) { bool valid = tile_ok;
;                 if (q == 0) valid = valid && (4 * fq + e >= fr);
;                 if (q == 8) valid = valid && (4 * fq + e <= fr);
;                 sc[q][e] = valid ? sc[q][e] : -INFINITY; mx = fmaxf(mx, sc[q][e]); } }
;         mx = fmaxf(mx, __shfl_xor(mx, 16)); mx = fmaxf(mx, __shfl_xor(mx, 32));
.Lapf_skip:
	s_waitcnt lgkmcnt(1)
	v_mfma_f32_16x16x32_bf16 v[52:55], v[52:55], v[60:63], 0
	s_and_b64 s[24:25], s[52:53], exec
	s_cselect_b32 s24, s46, s40
	v_lshl_or_b32 v0, s24, 7, v44
	v_mad_u64_u32 v[0:1], s[24:25], v0, s34, v[4:5]
	s_waitcnt lgkmcnt(0)
	v_mfma_f32_16x16x32_bf16 v[52:55], v[56:59], v[64:67], v[52:55]
	ds_read_b128 v[56:59], v0 offset:18432
	ds_read_b128 v[68:71], v0 offset:18496
	s_and_b64 s[24:25], s[54:55], exec
	s_cselect_b32 s42, s46, s40
	v_lshl_or_b32 v0, s42, 7, v45
	v_mad_u64_u32 v[0:1], s[24:25], v0, s34, v[4:5]
	s_waitcnt lgkmcnt(1)
	v_mfma_f32_16x16x32_bf16 v[56:59], v[56:59], v[60:63], 0
	ds_read_b128 v[72:75], v0 offset:18432
	s_and_b64 s[24:25], s[56:57], exec
	s_cselect_b32 s24, s46, s40
	s_waitcnt lgkmcnt(1)
	v_mfma_f32_16x16x32_bf16 v[56:59], v[68:71], v[64:67], v[56:59]
	ds_read_b128 v[68:71], v0 offset:18496
	v_lshl_or_b32 v0, s24, 7, v46
	v_mad_u64_u32 v[0:1], s[24:25], v0, s34, v[4:5]
	s_waitcnt lgkmcnt(1)
	v_mfma_f32_16x16x32_bf16 v[72:75], v[72:75], v[60:63], 0
	s_and_b64 s[24:25], s[58:59], exec
	s_cselect_b32 s47, s46, s40
	s_and_b64 s[24:25], s[60:61], exec
	s_waitcnt lgkmcnt(0)
	v_mfma_f32_16x16x32_bf16 v[68:71], v[68:71], v[64:67], v[72:75]
	s_nop 2
	ds_read_b128 v[72:75], v0 offset:18432
	ds_read_b128 v[76:79], v0 offset:18496
	v_lshl_or_b32 v0, s47, 7, v47
	v_mad_u64_u32 v[0:1], s[24:25], v0, s34, v[4:5]
	s_waitcnt lgkmcnt(1)
	v_mfma_f32_16x16x32_bf16 v[72:75], v[72:75], v[60:63], 0
	ds_read_b128 v[80:83], v0 offset:18432
	s_cselect_b32 s24, s46, s40
	s_waitcnt lgkmcnt(1)
	v_mfma_f32_16x16x32_bf16 v[72:75], v[76:79], v[64:67], v[72:75]
	ds_read_b128 v[76:79], v0 offset:18496
	v_lshl_or_b32 v0, s24, 7, v48
	v_mad_u64_u32 v[0:1], s[24:25], v0, s34, v[4:5]
	s_waitcnt lgkmcnt(1)
	v_mfma_f32_16x16x32_bf16 v[80:83], v[80:83], v[60:63], 0
	s_and_b64 s[24:25], s[62:63], exec
	s_cselect_b32 s25, s46, s40
	s_and_b64 vcc, s[64:65], exec
	s_waitcnt lgkmcnt(0)
	v_mfma_f32_16x16x32_bf16 v[76:79], v[76:79], v[64:67], v[80:83]
	s_nop 2
	ds_read_b128 v[80:83], v0 offset:18432
	ds_read_b128 v[84:87], v0 offset:18496
	v_lshl_or_b32 v0, s25, 7, v49
	v_mad_u64_u32 v[0:1], vcc, v0, s34, v[4:5]
	s_waitcnt lgkmcnt(1)
	v_mfma_f32_16x16x32_bf16 v[80:83], v[80:83], v[60:63], 0
	ds_read_b128 v[88:91], v0 offset:18432
	s_cselect_b32 s24, s46, s40
	s_and_b64 vcc, s[66:67], exec
	s_waitcnt lgkmcnt(1)
	v_mfma_f32_16x16x32_bf16 v[80:83], v[84:87], v[64:67], v[80:83]
	ds_read_b128 v[84:87], v0 offset:18496
	v_lshl_or_b32 v0, s24, 7, v50
	v_mad_u64_u32 v[0:1], vcc, v0, s34, v[4:5]
	s_waitcnt lgkmcnt(1)
	v_mfma_f32_16x16x32_bf16 v[88:91], v[88:91], v[60:63], 0
	s_cselect_b32 s24, s46, s40
	s_or_b64 s[26:27], s[2:3], s[68:69]
	s_waitcnt lgkmcnt(0)
	v_mfma_f32_16x16x32_bf16 v[84:87], v[84:87], v[64:67], v[88:91]
	s_nop 3
	ds_read_b128 v[88:91], v0 offset:18432
	ds_read_b128 v[92:95], v0 offset:18496
	v_lshl_or_b32 v0, s24, 7, v43
	v_mad_u64_u32 v[0:1], vcc, v0, s34, v[4:5]
	s_waitcnt lgkmcnt(1)
	v_mfma_f32_16x16x32_bf16 v[88:91], v[88:91], v[60:63], 0
	ds_read_b128 v[96:99], v0 offset:18432
	s_and_b64 vcc, s[26:27], s[8:9]
	s_waitcnt lgkmcnt(1)
	v_mfma_f32_16x16x32_bf16 v[88:91], v[92:95], v[64:67], v[88:91]
	ds_read_b128 v[92:95], v0 offset:18496
	s_waitcnt lgkmcnt(1)
	v_mfma_f32_16x16x32_bf16 v[60:63], v[96:99], v[60:63], 0
	s_waitcnt lgkmcnt(0)
	v_mfma_f32_16x16x32_bf16 v[60:63], v[92:95], v[64:67], v[60:63]
	v_cndmask_b32_e32 v64, v9, v52, vcc
	s_and_b64 vcc, s[26:27], s[10:11]
	v_cndmask_b32_e32 v65, v9, v53, vcc
	s_and_b64 vcc, s[26:27], s[12:13]
	v_cndmask_b32_e32 v54, v9, v54, vcc
	s_and_b64 vcc, s[26:27], s[14:15]
	v_max3_f32 v0, v64, s28, v65
	v_cndmask_b32_e32 v55, v9, v55, vcc
	s_or_b64 vcc, s[2:3], s[70:71]
	v_max3_f32 v0, v0, v54, v55
	v_cndmask_b32_e32 v56, v9, v56, vcc
	v_cndmask_b32_e32 v57, v9, v57, vcc
	v_max3_f32 v0, v0, v56, v57
	v_cndmask_b32_e32 v58, v9, v58, vcc
	v_cndmask_b32_e32 v59, v9, v59, vcc
	s_or_b64 vcc, s[2:3], s[72:73]
	v_max3_f32 v0, v0, v58, v59
	v_cndmask_b32_e32 v66, v9, v68, vcc
	v_cndmask_b32_e32 v67, v9, v69, vcc
	v_max3_f32 v0, v0, v66, v67
	v_cndmask_b32_e32 v68, v9, v70, vcc
	v_cndmask_b32_e32 v69, v9, v71, vcc
	s_or_b64 vcc, s[2:3], s[74:75]
	v_max3_f32 v0, v0, v68, v69
	v_cndmask_b32_e32 v70, v9, v72, vcc
	v_cndmask_b32_e32 v71, v9, v73, vcc
	v_max3_f32 v0, v0, v70, v71
	v_cndmask_b32_e32 v72, v9, v74, vcc
	v_cndmask_b32_e32 v73, v9, v75, vcc
	s_or_b64 vcc, s[2:3], s[76:77]
	v_max3_f32 v0, v0, v72, v73
	v_cndmask_b32_e32 v74, v9, v76, vcc
	v_cndmask_b32_e32 v75, v9, v77, vcc
	v_max3_f32 v0, v0, v74, v75
	v_cndmask_b32_e32 v76, v9, v78, vcc
	v_cndmask_b32_e32 v77, v9, v79, vcc
	s_or_b64 vcc, s[2:3], s[78:79]
	v_max3_f32 v0, v0, v76, v77
	v_cndmask_b32_e32 v78, v9, v80, vcc
	v_cndmask_b32_e32 v79, v9, v81, vcc
	v_max3_f32 v0, v0, v78, v79
	v_cndmask_b32_e32 v80, v9, v82, vcc
	v_cndmask_b32_e32 v81, v9, v83, vcc
	s_or_b64 vcc, s[2:3], s[80:81]
	v_max3_f32 v0, v0, v80, v81
	v_cndmask_b32_e32 v82, v9, v84, vcc
	v_cndmask_b32_e32 v83, v9, v85, vcc
	v_cndmask_b32_e32 v84, v9, v86, vcc
	v_cndmask_b32_e32 v85, v9, v87, vcc
	s_or_b64 vcc, s[2:3], s[82:83]
	s_or_b64 s[2:3], s[2:3], s[84:85]
	v_max3_f32 v0, v0, v82, v83
	v_cndmask_b32_e32 v86, v9, v88, vcc
	v_cndmask_b32_e32 v87, v9, v89, vcc
	v_cndmask_b32_e32 v88, v9, v90, vcc
	v_cndmask_b32_e32 v17, v9, v91, vcc
	s_and_b64 vcc, s[2:3], s[16:17]
	v_max3_f32 v0, v0, v84, v85
	v_cndmask_b32_e32 v53, v9, v60, vcc
	s_and_b64 vcc, s[2:3], s[18:19]
	v_max3_f32 v0, v0, v86, v87
	v_cndmask_b32_e32 v1, v9, v61, vcc
	s_and_b64 vcc, s[2:3], s[20:21]
	v_max3_f32 v0, v0, v88, v17
	v_cndmask_b32_e32 v2, v9, v62, vcc
	s_and_b64 vcc, s[2:3], s[22:23]
	v_max3_f32 v52, v0, v53, v1
	v_cndmask_b32_e32 v0, v9, v63, vcc
	v_max3_f32 v52, v52, v2, v0
	ds_bpermute_b32 v60, v7, v52
	s_lshl_b32 s26, s43, 8
	s_and_b64 s[2:3], s[86:87], exec
	s_cselect_b32 s2, s46, s40
	s_lshl_b32 s2, s2, 8
	s_waitcnt lgkmcnt(0)
; #define LAS __attribute__((address_space(3)))
; __device__ __forceinline__ unsigned pk2(float lo, float hi) { const f32x2 v = {lo, hi}; return __builtin_bit_cast(unsigned, __builtin_convertvector(v, bf16x2_hw)); }
;     ...
;         mx = fmaxf(mx, __shfl_xor(mx, 16)); mx = fmaxf(mx, __shfl_xor(mx, 32));
;         float l = 0.f;
; #pragma unroll
;         for (int q = 0; q < 9; ++q)
; #pragma unroll
;             for (int e = 0; e < 4; ++e) { sc[q][e] = __builtin_amdgcn_exp2f(sc[q][e] - mx); l += sc[q][e]; }
;         l += __shfl_xor(l, 16); l += __shfl_xor(l, 32);
;         f32x4 o[4];
; #pragma unroll
;         for (int dt = 0; dt < 4; ++dt) o[dt] = (f32x4){0.f, 0.f, 0.f, 0.f};
; #pragma unroll
;         for (int c = 0; c < 5; ++c) { const int jtA = w + 2 * c; int jtB = w + 2 * c + 1; jtB = jtB > 15 ? 15 : jtB;
;             const f32x4 pa = sc[2 * c]; const f32x4 pb = (2 * c + 1 <= 8) ? sc[(2 * c + 1 <= 8) ? 2 * c + 1 : 8] : (f32x4){0.f, 0.f, 0.f, 0.f};
;             u32x4 pw; pw.x = pk2(pa[0], pa[1]); pw.y = pk2(pa[2], pa[3]); pw.z = pk2(pb[0], pb[1]); pw.w = pk2(pb[2], pb[3]);
;             const bf16x8 bfrag = __builtin_bit_cast(bf16x8, pw);
; #pragma unroll
;             for (int dt = 0; dt < 4; ++dt) { const LAS bf16_t* vr = Vt + (16 * dt + fr) * VP + 4 * fq;
;                 const u32x2 lo = *(const LAS u32x2*)(vr + KOFF(jtA)), hi = *(const LAS u32x2*)(vr + KOFF(jtB)); const u32x4 av = {lo.x, lo.y, hi.x, hi.y};
;                 o[dt] = __builtin_amdgcn_mfma_f32_16x16x32_bf16(__builtin_bit_cast(bf16x8, av), bfrag, o[dt], 0, 0, 0); } }
	v_max_f32_e32 v60, v60, v60
	v_max_f32_e32 v52, v52, v60
	ds_bpermute_b32 v60, v18, v52
	s_waitcnt lgkmcnt(0)
	v_max_f32_e32 v60, v60, v60
	v_max_f32_e32 v52, v52, v60
	v_sub_f32_e32 v60, v64, v52
	v_exp_f32_e32 v60, v60
	v_sub_f32_e32 v61, v65, v52
	v_exp_f32_e32 v61, v61
	v_sub_f32_e32 v54, v54, v52
	v_exp_f32_e32 v62, v54
	v_sub_f32_e32 v55, v55, v52
	v_exp_f32_e32 v55, v55
	v_sub_f32_e32 v56, v56, v52
	v_add_f32_e32 v54, 0, v60
	v_exp_f32_e32 v56, v56
	v_sub_f32_e32 v57, v57, v52
	v_add_f32_e32 v54, v61, v54
	v_exp_f32_e32 v57, v57
	v_sub_f32_e32 v58, v58, v52
	v_add_f32_e32 v54, v62, v54
	v_exp_f32_e32 v63, v58
	v_sub_f32_e32 v58, v59, v52
	v_add_f32_e32 v54, v55, v54
	v_exp_f32_e32 v64, v58
	v_sub_f32_e32 v58, v66, v52
	v_add_f32_e32 v54, v56, v54
	v_exp_f32_e32 v89, v58
	v_sub_f32_e32 v58, v67, v52
	v_add_f32_e32 v54, v57, v54
	v_exp_f32_e32 v90, v58
	v_sub_f32_e32 v58, v68, v52
	v_add_f32_e32 v54, v63, v54
	v_exp_f32_e32 v91, v58
	v_sub_f32_e32 v58, v69, v52
	v_add_f32_e32 v54, v64, v54
	v_exp_f32_e32 v92, v58
	v_sub_f32_e32 v58, v70, v52
	v_add_f32_e32 v54, v89, v54
	v_exp_f32_e32 v93, v58
	v_sub_f32_e32 v58, v71, v52
	v_add_f32_e32 v54, v90, v54
	v_exp_f32_e32 v94, v58
	v_sub_f32_e32 v58, v72, v52
	v_add_f32_e32 v54, v91, v54
	v_exp_f32_e32 v95, v58
	v_sub_f32_e32 v58, v73, v52
	v_add_f32_e32 v54, v92, v54
	v_exp_f32_e32 v96, v58
	v_sub_f32_e32 v58, v74, v52
	v_add_f32_e32 v54, v93, v54
	v_exp_f32_e32 v97, v58
	v_sub_f32_e32 v58, v75, v52
	v_add_f32_e32 v54, v94, v54
	v_exp_f32_e32 v98, v58
	v_sub_f32_e32 v58, v76, v52
	v_add_f32_e32 v54, v95, v54
	v_exp_f32_e32 v99, v58
	v_sub_f32_e32 v58, v77, v52
	v_add_f32_e32 v54, v96, v54
	v_exp_f32_e32 v100, v58
	v_sub_f32_e32 v58, v78, v52
	v_add_f32_e32 v54, v97, v54
	v_exp_f32_e32 v101, v58
	v_sub_f32_e32 v58, v79, v52
	v_add_f32_e32 v54, v98, v54
	v_exp_f32_e32 v102, v58
	v_sub_f32_e32 v58, v80, v52
	v_add_f32_e32 v54, v99, v54
	v_exp_f32_e32 v103, v58
	v_sub_f32_e32 v58, v81, v52
	v_add_f32_e32 v54, v100, v54
	v_exp_f32_e32 v104, v58
	v_sub_f32_e32 v58, v82, v52
	v_add_f32_e32 v54, v101, v54
	v_exp_f32_e32 v105, v58
	v_sub_f32_e32 v58, v83, v52
	v_add_f32_e32 v54, v102, v54
	v_exp_f32_e32 v106, v58
	v_sub_f32_e32 v58, v84, v52
	v_add_f32_e32 v54, v103, v54
	v_exp_f32_e32 v107, v58
	v_add_f32_e32 v54, v104, v54
	v_sub_f32_e32 v70, v85, v52
	v_add_f32_e32 v54, v105, v54
	v_exp_f32_e32 v108, v70
	v_add_f32_e32 v54, v106, v54
	v_cvt_pk_bf16_f32 v55, v62, v55
	v_add_u32_e32 v62, s26, v19
	v_add_f32_e32 v74, v107, v54
	v_cvt_pk_bf16_f32 v54, v60, v61
	v_add_u32_e32 v65, s2, v20
	ds_read_b64 v[58:59], v62 offset:55296
	ds_read_b64 v[60:61], v65 offset:55296
	v_add_u32_e32 v71, s26, v21
	s_lshl_b32 s26, s42, 8
	v_add_u32_e32 v72, s2, v22
	s_and_b64 s[2:3], s[88:89], exec
	v_cvt_pk_bf16_f32 v56, v56, v57
	v_cvt_pk_bf16_f32 v57, v63, v64
	ds_read_b64 v[64:65], v65 offset:63744
	ds_read_b64 v[62:63], v62 offset:63744
	v_add_f32_e32 v109, v108, v74
	v_sub_f32_e32 v74, v86, v52
	s_cselect_b32 s2, s46, s40
	ds_read_b64 v[66:67], v71 offset:16896
	ds_read_b64 v[68:69], v72 offset:16896
	ds_read_b64 v[72:73], v72 offset:25344
	ds_read_b64 v[70:71], v71 offset:25344
	v_exp_f32_e32 v86, v74
	v_sub_f32_e32 v74, v87, v52
	s_lshl_b32 s2, s2, 8
	v_add_u32_e32 v78, s26, v23
	v_exp_f32_e32 v87, v74
	v_add_u32_e32 v79, s2, v24
	ds_read_b64 v[74:75], v78 offset:55296
	ds_read_b64 v[76:77], v79 offset:55296
	s_waitcnt lgkmcnt(8)
	v_mfma_f32_16x16x32_bf16 v[58:61], v[58:61], v[54:57], 0
	ds_read_b64 v[80:81], v79 offset:63744
	ds_read_b64 v[78:79], v78 offset:63744
	v_sub_f32_e32 v88, v88, v52
	v_exp_f32_e32 v88, v88
	s_waitcnt lgkmcnt(8)
	v_mfma_f32_16x16x32_bf16 v[62:65], v[62:65], v[54:57], 0
	v_sub_f32_e32 v17, v17, v52
	v_exp_f32_e32 v17, v17
	v_sub_f32_e32 v53, v53, v52
	s_waitcnt lgkmcnt(6)
	v_mfma_f32_16x16x32_bf16 v[66:69], v[66:69], v[54:57], 0
	v_exp_f32_e32 v53, v53
	v_sub_f32_e32 v1, v1, v52
	v_exp_f32_e32 v1, v1
	s_waitcnt lgkmcnt(4)
	v_mfma_f32_16x16x32_bf16 v[54:57], v[70:73], v[54:57], 0
	v_cvt_pk_bf16_f32 v70, v89, v90
	v_cvt_pk_bf16_f32 v71, v91, v92
	v_cvt_pk_bf16_f32 v72, v93, v94
	v_cvt_pk_bf16_f32 v73, v95, v96
	v_add_u32_e32 v89, s26, v25
	v_add_u32_e32 v90, s2, v26
	ds_read_b64 v[82:83], v89 offset:16896
	ds_read_b64 v[84:85], v90 offset:16896
	s_waitcnt lgkmcnt(4)
	v_mfma_f32_16x16x32_bf16 v[58:61], v[74:77], v[70:73], v[58:61]
	ds_read_b64 v[76:77], v90 offset:25344
	ds_read_b64 v[74:75], v89 offset:25344
	s_lshl_b32 s26, s47, 8
	s_and_b64 s[2:3], s[90:91], exec
	s_waitcnt lgkmcnt(4)
	v_mfma_f32_16x16x32_bf16 v[62:65], v[78:81], v[70:73], v[62:65]
	v_add_f32_e32 v78, v86, v109
	v_add_f32_e32 v78, v87, v78
	s_cselect_b32 s2, s46, s40
	v_add_f32_e32 v89, v88, v78
	s_lshl_b32 s2, s2, 8
	v_add_u32_e32 v78, s26, v27
	s_waitcnt lgkmcnt(0)
	v_mfma_f32_16x16x32_bf16 v[54:57], v[74:77], v[70:73], v[54:57]
	v_add_u32_e32 v79, s2, v28
	ds_read_b64 v[74:75], v78 offset:55296
	ds_read_b64 v[76:77], v79 offset:55296
	ds_read_b64 v[80:81], v79 offset:63744
	ds_read_b64 v[78:79], v78 offset:63744
	v_mfma_f32_16x16x32_bf16 v[66:69], v[82:85], v[70:73], v[66:69]
	v_cvt_pk_bf16_f32 v70, v97, v98
	v_cvt_pk_bf16_f32 v71, v99, v100
	v_cvt_pk_bf16_f32 v72, v101, v102
	v_cvt_pk_bf16_f32 v73, v103, v104
	v_add_u32_e32 v90, s26, v29
	v_add_u32_e32 v91, s2, v32
	ds_read_b64 v[82:83], v90 offset:16896
	ds_read_b64 v[84:85], v91 offset:16896
	s_waitcnt lgkmcnt(4)
; #define LAS __attribute__((address_space(3)))
; __device__ __forceinline__ unsigned pk2(float lo, float hi) { const f32x2 v = {lo, hi}; return __builtin_bit_cast(unsigned, __builtin_convertvector(v, bf16x2_hw)); }
;     ...
;         for (int c = 0; c < 5; ++c) { const int jtA = w + 2 * c; int jtB = w + 2 * c + 1; jtB = jtB > 15 ? 15 : jtB;
;             const f32x4 pa = sc[2 * c]; const f32x4 pb = (2 * c + 1 <= 8) ? sc[(2 * c + 1 <= 8) ? 2 * c + 1 : 8] : (f32x4){0.f, 0.f, 0.f, 0.f};
;             u32x4 pw; pw.x = pk2(pa[0], pa[1]); pw.y = pk2(pa[2], pa[3]); pw.z = pk2(pb[0], pb[1]); pw.w = pk2(pb[2], pb[3]);
;             const bf16x8 bfrag = __builtin_bit_cast(bf16x8, pw);
; #pragma unroll
;             for (int dt = 0; dt < 4; ++dt) { const LAS bf16_t* vr = Vt + (16 * dt + fr) * VP + 4 * fq;
;                 const u32x2 lo = *(const LAS u32x2*)(vr + KOFF(jtA)), hi = *(const LAS u32x2*)(vr + KOFF(jtB)); const u32x4 av = {lo.x, lo.y, hi.x, hi.y};
;                 o[dt] = __builtin_amdgcn_mfma_f32_16x16x32_bf16(__builtin_bit_cast(bf16x8, av), bfrag, o[dt], 0, 0, 0); } }
;         const float il = 1.0f / l; const int tq = tb + (128 * n + iq) * r;
;         bf16_t* op = (dry ? proj + (size_t)NT * NMAIN + (size_t)(tq & 63) * NMAIN : proj + (size_t)tq * NMAIN) + C_AQ + h * 64 + 4 * fq;
; #pragma unroll
;         for (int dt = 0; dt < 4; ++dt) { u32x2 wv; wv.x = pk2(o[dt][0] * il, o[dt][1] * il); wv.y = pk2(o[dt][2] * il, o[dt][3] * il); *(u32x2*)(op + 16 * dt) = wv; }
;         if (fq == 0) lse[((size_t)g * NT + tq) * 4 + hg] = mx * 0.6931471805599453f + __logf(l);
	v_mfma_f32_16x16x32_bf16 v[58:61], v[74:77], v[70:73], v[58:61]
	ds_read_b64 v[76:77], v91 offset:25344
	ds_read_b64 v[74:75], v90 offset:25344
	s_lshl_b32 s25, s25, 8
	s_and_b64 s[2:3], s[92:93], exec
	s_waitcnt lgkmcnt(4)
	v_mfma_f32_16x16x32_bf16 v[62:65], v[78:81], v[70:73], v[62:65]
	v_add_f32_e32 v78, v17, v89
	s_cselect_b32 s2, s46, s40
	v_add_f32_e32 v89, v53, v78
	s_lshl_b32 s2, s2, 8
	v_add_u32_e32 v78, s25, v33
	s_waitcnt lgkmcnt(0)
	v_mfma_f32_16x16x32_bf16 v[54:57], v[74:77], v[70:73], v[54:57]
	v_add_u32_e32 v79, s2, v34
	ds_read_b64 v[74:75], v78 offset:55296
	ds_read_b64 v[76:77], v79 offset:55296
	v_sub_f32_e32 v2, v2, v52
	v_mfma_f32_16x16x32_bf16 v[66:69], v[82:85], v[70:73], v[66:69]
	v_cvt_pk_bf16_f32 v73, v88, v17
	v_add_u32_e32 v17, s25, v35
	v_exp_f32_e32 v2, v2
	v_cvt_pk_bf16_f32 v72, v86, v87
	ds_read_b64 v[80:81], v79 offset:63744
	ds_read_b64 v[78:79], v78 offset:63744
	v_add_u32_e32 v86, s2, v36
	ds_read_b64 v[82:83], v17 offset:16896
	ds_read_b64 v[84:85], v86 offset:16896
	v_sub_f32_e32 v0, v0, v52
	v_exp_f32_e32 v88, v0
	v_cvt_pk_bf16_f32 v70, v105, v106
	v_cvt_pk_bf16_f32 v71, v107, v108
	s_lshl_b32 s24, s24, 8
	s_and_b64 s[2:3], s[94:95], exec
	s_waitcnt lgkmcnt(4)
	v_mfma_f32_16x16x32_bf16 v[58:61], v[74:77], v[70:73], v[58:61]
	v_add_f32_e32 v74, v1, v89
	v_add_f32_e32 v87, v2, v74
	s_cselect_b32 s2, s46, s40
	ds_read_b64 v[76:77], v86 offset:25344
	ds_read_b64 v[74:75], v17 offset:25344
	s_waitcnt lgkmcnt(2)
	v_mfma_f32_16x16x32_bf16 v[66:69], v[82:85], v[70:73], v[66:69]
	s_lshl_b32 s2, s2, 8
	v_add_u32_e32 v17, s24, v19
	v_add_f32_e32 v83, v88, v87
	v_mfma_f32_16x16x32_bf16 v[62:65], v[78:81], v[70:73], v[62:65]
	v_add_u32_e32 v82, s2, v37
	ds_read_b64 v[78:79], v17 offset:55296
	ds_read_b64 v[80:81], v82 offset:55296
	ds_bpermute_b32 v84, v7, v83
	v_cvt_pk_bf16_f32 v0, v53, v1
	v_cvt_pk_bf16_f32 v1, v2, v88
	v_mov_b32_e32 v2, v3
	s_waitcnt lgkmcnt(3)
	v_mfma_f32_16x16x32_bf16 v[54:57], v[74:77], v[70:73], v[54:57]
	ds_read_b64 v[72:73], v82 offset:63744
	ds_read_b64 v[70:71], v17 offset:63744
	v_add_u32_e32 v17, s24, v21
	v_add_u32_e32 v53, s2, v38
	s_waitcnt lgkmcnt(3)
	v_mfma_f32_16x16x32_bf16 v[58:61], v[78:81], v[0:3], v[58:61]
	s_waitcnt lgkmcnt(2)
	v_add_f32_e32 v78, v83, v84
	ds_bpermute_b32 v79, v18, v78
	ds_read_b64 v[74:75], v17 offset:16896
	ds_read_b64 v[76:77], v53 offset:16896
	s_waitcnt lgkmcnt(3)
	v_mfma_f32_16x16x32_bf16 v[62:65], v[70:73], v[0:3], v[62:65]
	ds_read_b64 v[72:73], v53 offset:25344
	ds_read_b64 v[70:71], v17 offset:25344
	s_waitcnt lgkmcnt(4)
	v_add_f32_e32 v53, v78, v79
	v_div_scale_f32 v17, s[2:3], v53, v53, 1.0
	s_waitcnt lgkmcnt(2)
	v_mfma_f32_16x16x32_bf16 v[66:69], v[74:77], v[0:3], v[66:69]
	v_rcp_f32_e32 v74, v17
	s_waitcnt lgkmcnt(0)
	v_mfma_f32_16x16x32_bf16 v[54:57], v[70:73], v[0:3], v[54:57]
	v_fma_f32 v0, -v17, v74, 1.0
	v_fmac_f32_e32 v74, v0, v74
	v_div_scale_f32 v0, vcc, 1.0, v53, 1.0
	v_mul_f32_e32 v1, v0, v74
	v_fma_f32 v2, -v17, v1, v0
	v_fmac_f32_e32 v1, v2, v74
	v_fma_f32 v0, -v17, v1, v0
	v_div_fmas_f32 v0, v0, v74, v1
	v_div_fixup_f32 v2, v0, v53, 1.0
	v_add_u32_e32 v0, s45, v5
	v_lshlrev_b32_e32 v0, s97, v0
	v_add_u32_e32 v0, s44, v0
	v_mov_b64_e32 v[70:71], s[48:49]
	v_mad_i64_i32 v[70:71], s[2:3], v0, s35, v[70:71]
	v_lshl_add_u64 v[70:71], s[0:1], 1, v[70:71]
	v_mov_b32_e32 v17, v3
	v_lshl_add_u64 v[70:71], v[70:71], 0, v[16:17]
	v_pk_mul_f32 v[58:59], v[2:3], v[58:59] op_sel_hi:[0,1]
	v_pk_mul_f32 v[60:61], v[2:3], v[60:61] op_sel_hi:[0,1]
	v_cvt_pk_bf16_f32 v58, v58, v59
	v_cvt_pk_bf16_f32 v59, v60, v61
	v_add_co_u32_e32 v60, vcc, s29, v70
	s_mov_b64 s[0:1], 0x1800
	s_nop 0
	v_addc_co_u32_e32 v61, vcc, 0, v71, vcc
	global_store_dwordx2 v[60:61], v[58:59], off offset:2048
	v_pk_mul_f32 v[58:59], v[2:3], v[62:63] op_sel_hi:[0,1]
	v_pk_mul_f32 v[60:61], v[2:3], v[64:65] op_sel_hi:[0,1]
	v_lshl_add_u64 v[72:73], v[70:71], 0, s[0:1]
	v_cvt_pk_bf16_f32 v58, v58, v59
	v_cvt_pk_bf16_f32 v59, v60, v61
	global_store_dwordx2 v[72:73], v[58:59], off offset:32
	v_pk_mul_f32 v[58:59], v[2:3], v[66:67] op_sel_hi:[0,1]
	v_pk_mul_f32 v[60:61], v[2:3], v[68:69] op_sel_hi:[0,1]
	v_pk_mul_f32 v[54:55], v[2:3], v[54:55] op_sel_hi:[0,1]
	v_pk_mul_f32 v[56:57], v[2:3], v[56:57] op_sel_hi:[0,1]
	v_cvt_pk_bf16_f32 v58, v58, v59
	v_cvt_pk_bf16_f32 v59, v60, v61
	v_cvt_pk_bf16_f32 v54, v54, v55
	v_cvt_pk_bf16_f32 v55, v56, v57
	global_store_dwordx2 v[72:73], v[58:59], off offset:64
	global_store_dwordx2 v[72:73], v[54:55], off offset:96
	s_mov_b32 s98, 4
	s_and_saveexec_b64 s[0:1], s[6:7]
	s_cbranch_execz .LBB0_331
	v_cmp_gt_f32_e32 vcc, s31, v53
	s_ashr_i32 s97, s96, 31
	s_lshl_b64 s[2:3], s[96:97], 18
	v_cndmask_b32_e64 v1, 0, 32, vcc
	v_ldexp_f32 v1, v53, v1
	v_log_f32_e32 v2, v1
	s_add_u32 s2, s5, s2
	v_ashrrev_i32_e32 v1, 31, v0
	v_cndmask_b32_e32 v17, 0, v30, vcc
	v_mul_f32_e32 v53, 0x3f317217, v2
	v_fma_f32 v53, v2, s36, -v53
	v_fmac_f32_e32 v53, 0x3377d1cf, v2
	v_fmac_f32_e32 v53, 0x3f317217, v2
	v_cmp_lt_f32_e64 vcc, |v2|, s37
	s_addc_u32 s3, s33, s3
	v_lshl_add_u64 v[0:1], v[0:1], 4, s[2:3]
	v_cndmask_b32_e32 v2, v2, v53, vcc
	s_lshr_b32 s2, s38, 3
	v_sub_f32_e32 v2, v2, v17
	s_and_b32 s38, s2, 12
	v_fmac_f32_e32 v2, 0x3f317218, v52
	v_lshl_add_u64 v[0:1], v[0:1], 0, s[38:39]
	global_store_dword v[0:1], v2, off
	s_mov_b32 s98, 5
	s_branch .LBB0_331
